# FoX loop (single barrier, no stagger): 5 of the 8 PV MFMAs moved down into the sub/exp block, in-place sub/exp, scalar row-sum tree, rescale after the sums, no register-rotation copies
# speedup vs baseline: 1.0007x; 1.0007x over previous
.LBB0_170:
	v_pk_add_f32 v[6:7], v[10:11], v[6:7] op_sel_hi:[0,1]
	v_pk_add_f32 v[8:9], v[10:11], v[8:9] op_sel_hi:[0,1]
	v_xor_b32_e32 v7, 0x80000000, v7
	v_xor_b32_e32 v6, 0x80000000, v6
	v_xor_b32_e32 v9, 0x80000000, v9
	v_xor_b32_e32 v8, 0x80000000, v8
	v_pk_add_f32 v[4:5], v[10:11], v[4:5] op_sel_hi:[0,1]
	v_pk_add_f32 v[2:3], v[10:11], v[2:3] op_sel_hi:[0,1]
	ds_write_b128 v185, v[6:9]
	v_xor_b32_e32 v5, 0x80000000, v5
	v_xor_b32_e32 v4, 0x80000000, v4
	v_xor_b32_e32 v7, 0x80000000, v3
	v_xor_b32_e32 v6, 0x80000000, v2
	ds_write_b128 v185, v[4:7] offset:16
	v_or_b32_e32 v4, s37, v188
	v_ashrrev_i32_e32 v5, 31, v4
	s_lshl_b32 s38, s44, 6
	s_lshl_b32 s39, s43, 10
	v_lshlrev_b64 v[4:5], 12, v[4:5]
	s_lshl_b32 s78, s44, 7
	s_or_b32 s38, s38, s39
	v_lshl_add_u64 v[4:5], s[96:97], 0, v[4:5]
	v_add_u32_e32 v2, s38, v187
	v_lshl_add_u64 v[4:5], v[4:5], 0, s[78:79]
	v_mov_b32_e32 v175, v0
	v_ashrrev_i32_e32 v3, 31, v2
	v_lshl_add_u64 v[4:5], v[4:5], 0, v[174:175]
	v_lshlrev_b64 v[2:3], 13, v[2:3]
	v_lshl_add_u64 v[4:5], s[34:35], 1, v[4:5]
	s_mov_b64 s[38:39], 0x800
	v_lshl_add_u64 v[2:3], v[170:171], 0, v[2:3]
	v_lshl_add_u64 v[4:5], v[4:5], 0, s[38:39]
	s_and_b32 s42, s33, 1
	v_add_u32_e32 v205, s37, v186
	v_lshl_add_u64 v[176:177], v[168:169], 0, s[78:79]
	v_lshl_add_u64 v[178:179], v[172:173], 0, s[78:79]
	v_cndmask_b32_e64 v181, v3, v5, s[4:5]
	v_cndmask_b32_e64 v180, v2, v4, s[4:5]
	s_mov_b32 s43, 0
	s_waitcnt lgkmcnt(0)
	s_barrier
	s_branch .LBB0_172
.LBB0_171:
	v_mfma_f32_32x32x16_bf16 v[18:33], v[158:161], v[122:125], v[18:33]
	ds_bpermute_b32 v1, v203, v206
	v_lshlrev_b64 v[36:37], 11, v[182:183]
	v_lshl_add_u64 v[36:37], v[178:179], 0, v[36:37]
	s_waitcnt lgkmcnt(0)
	v_add_f32_e32 v1, v206, v1
	v_rcp_f32_e32 v34, v1
	v_mfma_f32_32x32x16_bf16 v[2:17], v[142:145], v[122:125], v[2:17]
	v_mfma_f32_32x32x16_bf16 v[18:33], v[154:157], v[118:121], v[18:33]
	v_mfma_f32_32x32x16_bf16 v[2:17], v[138:141], v[118:121], v[2:17]
	v_mfma_f32_32x32x16_bf16 v[18:33], v[150:153], v[114:117], v[18:33]
	v_mfma_f32_32x32x16_bf16 v[2:17], v[134:137], v[114:117], v[2:17]
	v_mfma_f32_32x32x16_bf16 v[18:33], v[146:149], v[110:113], v[18:33]
	v_mfma_f32_32x32x16_bf16 v[2:17], v[130:133], v[110:113], v[2:17]
	s_nop 10
	v_mul_f32_e64 v18, v18, v34
	v_mul_f32_e64 v19, v19, v34
	v_mul_f32_e64 v20, v20, v34
	v_mul_f32_e64 v21, v21, v34
	v_cvt_pk_bf16_f32 v18, v18, v19
	v_cvt_pk_bf16_f32 v19, v20, v21
	global_store_dwordx2 v[36:37], v[18:19], off
	v_pk_mul_f32 v[18:19], v[22:23], v[34:35] op_sel_hi:[1,0]
	v_pk_mul_f32 v[20:21], v[24:25], v[34:35] op_sel_hi:[1,0]
	v_pk_mul_f32 v[2:3], v[2:3], v[34:35] op_sel_hi:[1,0]
	v_pk_mul_f32 v[4:5], v[4:5], v[34:35] op_sel_hi:[1,0]
	v_cvt_pk_bf16_f32 v2, v2, v3
	v_cvt_pk_bf16_f32 v3, v4, v5
	global_store_dwordx2 v[36:37], v[2:3], off offset:64
	v_pk_mul_f32 v[2:3], v[6:7], v[34:35] op_sel_hi:[1,0]
	v_pk_mul_f32 v[4:5], v[8:9], v[34:35] op_sel_hi:[1,0]
	v_cvt_pk_bf16_f32 v18, v18, v19
	v_cvt_pk_bf16_f32 v19, v20, v21
	v_cvt_pk_bf16_f32 v2, v2, v3
	v_cvt_pk_bf16_f32 v3, v4, v5
	global_store_dwordx2 v[36:37], v[18:19], off offset:16
	v_pk_mul_f32 v[18:19], v[26:27], v[34:35] op_sel_hi:[1,0]
	v_pk_mul_f32 v[20:21], v[28:29], v[34:35] op_sel_hi:[1,0]
	global_store_dwordx2 v[36:37], v[2:3], off offset:80
	v_pk_mul_f32 v[2:3], v[10:11], v[34:35] op_sel_hi:[1,0]
	v_pk_mul_f32 v[4:5], v[12:13], v[34:35] op_sel_hi:[1,0]
	v_cvt_pk_bf16_f32 v18, v18, v19
	v_cvt_pk_bf16_f32 v19, v20, v21
	v_cvt_pk_bf16_f32 v2, v2, v3
	v_cvt_pk_bf16_f32 v3, v4, v5
	global_store_dwordx2 v[36:37], v[18:19], off offset:32
	v_pk_mul_f32 v[18:19], v[30:31], v[34:35] op_sel_hi:[1,0]
	v_pk_mul_f32 v[20:21], v[32:33], v[34:35] op_sel_hi:[1,0]
	global_store_dwordx2 v[36:37], v[2:3], off offset:96
	v_pk_mul_f32 v[2:3], v[14:15], v[34:35] op_sel_hi:[1,0]
	v_pk_mul_f32 v[4:5], v[16:17], v[34:35] op_sel_hi:[1,0]
	v_cvt_pk_bf16_f32 v18, v18, v19
	v_cvt_pk_bf16_f32 v19, v20, v21
	v_cvt_pk_bf16_f32 v2, v2, v3
	v_cvt_pk_bf16_f32 v3, v4, v5
	global_store_dwordx2 v[36:37], v[18:19], off offset:48
	global_store_dwordx2 v[36:37], v[2:3], off offset:112
	s_setprio 0
	s_waitcnt lgkmcnt(0)
	s_barrier
	s_add_i32 s43, s43, 1
	s_cmp_eq_u32 s43, 8
	s_cbranch_scc1 .LBB0_164

.LBB0_183:
	ds_read_b128 v[34:37], v175
	ds_read_b128 v[38:41], v175 offset:16
	ds_read_b128 v[42:45], v175 offset:64
	ds_read_b128 v[46:49], v175 offset:80
	ds_read_b128 v[50:53], v175 offset:128
	ds_read_b128 v[54:57], v175 offset:144
	ds_read_b128 v[58:61], v175 offset:192
	ds_read_b128 v[62:65], v175 offset:208
	s_add_i32 s37, s49, 0x18000
	s_waitcnt lgkmcnt(4)
	v_mfma_f32_32x32x16_bf16 v[34:49], v[126:129], v[66:69], v[34:49]
	s_and_b32 s37, s37, 0xc000
	v_add_u32_e32 v1, s37, v189
	s_andn2_b64 vcc, exec, s[38:39]
	s_waitcnt lgkmcnt(0)
	v_mfma_f32_32x32x16_bf16 v[50:65], v[106:109], v[66:69], v[50:65]
	v_mfma_f32_32x32x16_bf16 v[34:49], v[98:101], v[70:73], v[34:49]
	ds_read_b128 v[126:129], v1 offset:32768
	v_mfma_f32_32x32x16_bf16 v[50:65], v[102:105], v[70:73], v[50:65]
	ds_read_b128 v[106:109], v1 offset:40960
	v_mfma_f32_32x32x16_bf16 v[34:49], v[86:89], v[74:77], v[34:49]
	ds_read_b128 v[98:101], v1 offset:33792
	ds_read_b128 v[102:105], v1 offset:41984
	v_mfma_f32_32x32x16_bf16 v[50:65], v[94:97], v[74:77], v[50:65]
	ds_read_b128 v[86:89], v1 offset:34816
	v_mfma_f32_32x32x16_bf16 v[34:49], v[82:85], v[78:81], v[34:49]
	ds_read_b128 v[94:97], v1 offset:43008
	ds_read_b128 v[82:85], v1 offset:35840
	v_mfma_f32_32x32x16_bf16 v[50:65], v[90:93], v[78:81], v[50:65]
	ds_read_b128 v[90:93], v1 offset:44032
	s_cbranch_vccnz .LBB0_185
	v_add_u32_e32 v1, s50, v166
	v_add_u32_e32 v163, 0xe0, v1
	v_add_u32_e32 v162, 0xc0, v1
	v_cmp_le_i32_e32 vcc, v163, v186
	s_nop 6
	v_cndmask_b32_e32 v50, v239, v50, vcc
	v_cmp_lt_i32_e32 vcc, v162, v186
	s_nop 1
	v_cndmask_b32_e32 v35, v239, v35, vcc
	v_cmp_le_i32_e32 vcc, v162, v186
	v_add_u32_e32 v162, 0xe1, v1
	s_nop 0
	v_cndmask_b32_e32 v34, v239, v34, vcc
	v_cmp_le_i32_e32 vcc, v162, v186
	v_add_u32_e32 v162, 0xc2, v1
	s_nop 0
	v_cndmask_b32_e32 v51, v239, v51, vcc
	v_cmp_le_i32_e32 vcc, v162, v186
	v_add_u32_e32 v162, 0xe2, v1
	s_nop 0
	v_cndmask_b32_e32 v36, v239, v36, vcc
	v_cmp_le_i32_e32 vcc, v162, v186
	v_add_u32_e32 v162, 0xc3, v1
	s_nop 0
	v_cndmask_b32_e32 v52, v239, v52, vcc
	v_cmp_le_i32_e32 vcc, v162, v186
	v_add_u32_e32 v162, 0xe3, v1
	s_nop 0
	v_cndmask_b32_e32 v37, v239, v37, vcc
	v_cmp_le_i32_e32 vcc, v162, v186
	v_add_u32_e32 v162, 0xc4, v1
	s_nop 0
	v_cndmask_b32_e32 v53, v239, v53, vcc
	v_cmp_le_i32_e32 vcc, v162, v186
	v_add_u32_e32 v162, 0xe4, v1
	s_nop 0
	v_cndmask_b32_e32 v38, v239, v38, vcc
	v_cmp_le_i32_e32 vcc, v162, v186
	v_add_u32_e32 v162, 0xc5, v1
	s_nop 0
	v_cndmask_b32_e32 v54, v239, v54, vcc
	v_cmp_le_i32_e32 vcc, v162, v186
	v_add_u32_e32 v162, 0xe5, v1
	s_nop 0
	v_cndmask_b32_e32 v39, v239, v39, vcc
	v_cmp_le_i32_e32 vcc, v162, v186
	v_add_u32_e32 v162, 0xc6, v1
	s_nop 0
	v_cndmask_b32_e32 v55, v239, v55, vcc
	v_cmp_le_i32_e32 vcc, v162, v186
	v_add_u32_e32 v162, 0xe6, v1
	s_nop 0
	v_cndmask_b32_e32 v40, v239, v40, vcc
	v_cmp_le_i32_e32 vcc, v162, v186
	v_add_u32_e32 v162, 0xc7, v1
	s_nop 0
	v_cndmask_b32_e32 v56, v239, v56, vcc
	v_cmp_le_i32_e32 vcc, v162, v186
	v_add_u32_e32 v162, 0xe7, v1
	s_nop 0
	v_cndmask_b32_e32 v41, v239, v41, vcc
	v_cmp_le_i32_e32 vcc, v162, v186
	v_add_u32_e32 v162, 0xd0, v1
	s_nop 0
	v_cndmask_b32_e32 v57, v239, v57, vcc
	v_cmp_le_i32_e32 vcc, v162, v186
	v_add_u32_e32 v162, 0xf0, v1
	s_nop 0
	v_cndmask_b32_e32 v42, v239, v42, vcc
	v_cmp_le_i32_e32 vcc, v162, v186
	v_add_u32_e32 v162, 0xd1, v1
	s_nop 0
	v_cndmask_b32_e32 v58, v239, v58, vcc
	v_cmp_le_i32_e32 vcc, v162, v186
	v_add_u32_e32 v162, 0xf1, v1
	s_nop 0
	v_cndmask_b32_e32 v43, v239, v43, vcc
	v_cmp_le_i32_e32 vcc, v162, v186
	v_add_u32_e32 v162, 0xd2, v1
	s_nop 0
	v_cndmask_b32_e32 v59, v239, v59, vcc
	v_cmp_le_i32_e32 vcc, v162, v186
	v_add_u32_e32 v162, 0xf2, v1
	s_nop 0
	v_cndmask_b32_e32 v44, v239, v44, vcc
	v_cmp_le_i32_e32 vcc, v162, v186
	v_add_u32_e32 v162, 0xd3, v1
	s_nop 0
	v_cndmask_b32_e32 v60, v239, v60, vcc
	v_cmp_le_i32_e32 vcc, v162, v186
	v_add_u32_e32 v162, 0xf3, v1
	s_nop 0
	v_cndmask_b32_e32 v45, v239, v45, vcc
	v_cmp_le_i32_e32 vcc, v162, v186
	v_add_u32_e32 v162, 0xd4, v1
	s_nop 0
	v_cndmask_b32_e32 v61, v239, v61, vcc
	v_cmp_le_i32_e32 vcc, v162, v186
	v_add_u32_e32 v162, 0xf4, v1
	s_nop 0
	v_cndmask_b32_e32 v46, v239, v46, vcc
	v_cmp_le_i32_e32 vcc, v162, v186
	v_add_u32_e32 v162, 0xd5, v1
	s_nop 0
	v_cndmask_b32_e32 v62, v239, v62, vcc
	v_cmp_le_i32_e32 vcc, v162, v186
	v_add_u32_e32 v162, 0xf5, v1
	s_nop 0
	v_cndmask_b32_e32 v47, v239, v47, vcc
	v_cmp_le_i32_e32 vcc, v162, v186
	v_add_u32_e32 v162, 0xd6, v1
	s_nop 0
	v_cndmask_b32_e32 v63, v239, v63, vcc
	v_cmp_le_i32_e32 vcc, v162, v186
	v_add_u32_e32 v162, 0xf6, v1
	s_nop 0
	v_cndmask_b32_e32 v48, v239, v48, vcc
	v_cmp_le_i32_e32 vcc, v162, v186
	v_add_u32_e32 v162, 0xd7, v1
	v_add_u32_e32 v1, 0xf7, v1
	v_cndmask_b32_e32 v64, v239, v64, vcc
	v_cmp_le_i32_e32 vcc, v162, v186
	s_nop 1
	v_cndmask_b32_e32 v49, v239, v49, vcc
	v_cmp_le_i32_e32 vcc, v1, v186
	s_nop 1
	v_cndmask_b32_e32 v65, v239, v65, vcc
.LBB0_185:
	v_mfma_f32_32x32x16_bf16 v[18:33], v[158:161], v[122:125], v[18:33]
	s_add_i32 s37, s49, 0xc000
	s_and_b32 s37, s37, 0xc000
	v_add_u32_e32 v194, s37, v189
	s_nop 3
	v_max3_f32 v1, v34, v35, v36
	ds_read_b128 v[158:161], v194 offset:36864
	v_max3_f32 v1, v1, v37, v38
	v_max3_f32 v1, v1, v39, v40
	v_max3_f32 v1, v1, v41, v42
	v_mfma_f32_32x32x16_bf16 v[18:33], v[154:157], v[118:121], v[18:33]
	v_max3_f32 v1, v1, v43, v44
	ds_read_b128 v[154:157], v194 offset:37888
	v_max3_f32 v1, v1, v45, v46
	v_max3_f32 v1, v1, v47, v48
	v_max3_f32 v162, v50, v51, v52
	v_mfma_f32_32x32x16_bf16 v[2:17], v[142:145], v[122:125], v[2:17]
	v_max3_f32 v162, v162, v53, v54
	ds_read_b128 v[142:145], v194 offset:38912
	v_max3_f32 v162, v162, v55, v56
	v_max3_f32 v162, v162, v57, v58
	v_max3_f32 v162, v162, v59, v60
	v_max3_f32 v162, v162, v61, v62
	v_max3_f32 v162, v162, v63, v64
	v_max3_f32 v162, v162, v65, v49
	v_max_f32_e32 v1, v1, v162
	ds_bpermute_b32 v163, v203, v1
	v_mfma_f32_32x32x16_bf16 v[18:33], v[150:153], v[114:117], v[18:33]
	v_mfma_f32_32x32x16_bf16 v[2:17], v[138:141], v[118:121], v[2:17]
	s_waitcnt lgkmcnt(0)
	v_max3_f32 v1, v207, v1, v163
	ds_read_b128 v[150:153], v194 offset:45056
	ds_read_b128 v[138:141], v194 offset:39936
	v_sub_f32_e32 v164, v207, v1
	v_exp_f32_e32 v164, v164
	v_sub_f32_e32 v34, v34, v1
	v_sub_f32_e32 v35, v35, v1
	v_sub_f32_e32 v36, v36, v1
	v_sub_f32_e32 v37, v37, v1
	v_sub_f32_e32 v38, v38, v1
	v_sub_f32_e32 v39, v39, v1
	v_sub_f32_e32 v40, v40, v1
	v_sub_f32_e32 v41, v41, v1
	v_mfma_f32_32x32x16_bf16 v[18:33], v[146:149], v[110:113], v[18:33]
	v_sub_f32_e32 v42, v42, v1
	v_sub_f32_e32 v43, v43, v1
	v_sub_f32_e32 v44, v44, v1
	v_sub_f32_e32 v45, v45, v1
	v_sub_f32_e32 v46, v46, v1
	v_sub_f32_e32 v47, v47, v1
	v_sub_f32_e32 v48, v48, v1
	v_sub_f32_e32 v49, v49, v1
	ds_read_b128 v[146:149], v194 offset:46080
	v_exp_f32_e32 v34, v34
	v_exp_f32_e32 v35, v35
	v_exp_f32_e32 v36, v36
	v_exp_f32_e32 v37, v37
	v_exp_f32_e32 v38, v38
	v_exp_f32_e32 v39, v39
	v_exp_f32_e32 v40, v40
	v_exp_f32_e32 v41, v41
	v_mfma_f32_32x32x16_bf16 v[2:17], v[134:137], v[114:117], v[2:17]
	v_sub_f32_e32 v50, v50, v1
	v_sub_f32_e32 v51, v51, v1
	v_sub_f32_e32 v52, v52, v1
	v_sub_f32_e32 v53, v53, v1
	v_sub_f32_e32 v54, v54, v1
	v_sub_f32_e32 v55, v55, v1
	v_sub_f32_e32 v56, v56, v1
	v_sub_f32_e32 v57, v57, v1
	ds_read_b128 v[134:137], v194 offset:47104
	v_exp_f32_e32 v42, v42
	v_exp_f32_e32 v43, v43
	v_exp_f32_e32 v44, v44
	v_exp_f32_e32 v45, v45
	v_exp_f32_e32 v46, v46
	v_exp_f32_e32 v47, v47
	v_exp_f32_e32 v48, v48
	v_exp_f32_e32 v49, v49
	v_mfma_f32_32x32x16_bf16 v[2:17], v[130:133], v[110:113], v[2:17]
	v_sub_f32_e32 v58, v58, v1
	v_sub_f32_e32 v59, v59, v1
	v_sub_f32_e32 v60, v60, v1
	v_sub_f32_e32 v61, v61, v1
	v_sub_f32_e32 v62, v62, v1
	v_sub_f32_e32 v63, v63, v1
	v_sub_f32_e32 v64, v64, v1
	v_sub_f32_e32 v65, v65, v1
	ds_read_b128 v[130:133], v194 offset:48128
	v_exp_f32_e32 v50, v50
	v_exp_f32_e32 v51, v51
	v_exp_f32_e32 v52, v52
	v_exp_f32_e32 v53, v53
	v_exp_f32_e32 v54, v54
	v_exp_f32_e32 v55, v55
	v_exp_f32_e32 v56, v56
	v_exp_f32_e32 v57, v57
	v_exp_f32_e32 v58, v58
	v_exp_f32_e32 v59, v59
	v_exp_f32_e32 v60, v60
	v_exp_f32_e32 v61, v61
	v_exp_f32_e32 v62, v62
	v_exp_f32_e32 v63, v63
	v_exp_f32_e32 v64, v64
	v_exp_f32_e32 v65, v65
	v_add_f32_e32 v110, v34, v35
	v_add_f32_e32 v111, v36, v37
	v_add_f32_e32 v112, v38, v39
	v_add_f32_e32 v113, v40, v41
	v_add_f32_e32 v110, v42, v110
	v_add_f32_e32 v111, v43, v111
	v_add_f32_e32 v112, v44, v112
	v_add_f32_e32 v113, v45, v113
	v_add_f32_e32 v110, v46, v110
	v_add_f32_e32 v111, v47, v111
	v_add_f32_e32 v112, v48, v112
	v_add_f32_e32 v113, v49, v113
	v_add_f32_e32 v110, v50, v110
	v_add_f32_e32 v111, v51, v111
	v_add_f32_e32 v112, v52, v112
	v_add_f32_e32 v113, v53, v113
	v_add_f32_e32 v110, v54, v110
	v_add_f32_e32 v111, v55, v111
	v_add_f32_e32 v112, v56, v112
	v_add_f32_e32 v113, v57, v113
	v_add_f32_e32 v110, v58, v110
	v_add_f32_e32 v111, v59, v111
	v_add_f32_e32 v112, v60, v112
	v_add_f32_e32 v113, v61, v113
	v_add_f32_e32 v110, v62, v110
	v_add_f32_e32 v111, v63, v111
	v_add_f32_e32 v112, v64, v112
	v_add_f32_e32 v113, v65, v113
	v_add_f32_e32 v110, v110, v111
	v_add_f32_e32 v112, v112, v113
	v_add_f32_e32 v162, v110, v112
	v_cmp_neq_f32_e32 vcc, 1.0, v164
	s_cbranch_vccz .Lfx_norescale
	v_pk_mul_f32 v[32:33], v[32:33], v[164:165] op_sel_hi:[1,0]
	v_pk_mul_f32 v[30:31], v[30:31], v[164:165] op_sel_hi:[1,0]
	v_pk_mul_f32 v[28:29], v[28:29], v[164:165] op_sel_hi:[1,0]
	v_pk_mul_f32 v[26:27], v[26:27], v[164:165] op_sel_hi:[1,0]
	v_pk_mul_f32 v[24:25], v[24:25], v[164:165] op_sel_hi:[1,0]
	v_pk_mul_f32 v[22:23], v[22:23], v[164:165] op_sel_hi:[1,0]
	v_pk_mul_f32 v[20:21], v[20:21], v[164:165] op_sel_hi:[1,0]
	v_pk_mul_f32 v[18:19], v[18:19], v[164:165] op_sel_hi:[1,0]
	v_pk_mul_f32 v[16:17], v[16:17], v[164:165] op_sel_hi:[1,0]
	v_pk_mul_f32 v[14:15], v[14:15], v[164:165] op_sel_hi:[1,0]
	v_pk_mul_f32 v[12:13], v[12:13], v[164:165] op_sel_hi:[1,0]
	v_pk_mul_f32 v[10:11], v[10:11], v[164:165] op_sel_hi:[1,0]
	v_pk_mul_f32 v[8:9], v[8:9], v[164:165] op_sel_hi:[1,0]
	v_pk_mul_f32 v[6:7], v[6:7], v[164:165] op_sel_hi:[1,0]
	v_pk_mul_f32 v[4:5], v[4:5], v[164:165] op_sel_hi:[1,0]
	v_pk_mul_f32 v[2:3], v[2:3], v[164:165] op_sel_hi:[1,0]
.Lfx_norescale:
	v_fma_f32 v206, v206, v164, v162
	v_cvt_pk_bf16_f32 v122, v34, v35
	v_cvt_pk_bf16_f32 v123, v36, v37
	v_cvt_pk_bf16_f32 v124, v38, v39
	v_cvt_pk_bf16_f32 v125, v40, v41
	v_cvt_pk_bf16_f32 v118, v42, v43
	v_cvt_pk_bf16_f32 v119, v44, v45
	v_cvt_pk_bf16_f32 v120, v46, v47
	v_cvt_pk_bf16_f32 v121, v48, v49
	v_cvt_pk_bf16_f32 v114, v50, v51
	v_cvt_pk_bf16_f32 v115, v52, v53
	v_cvt_pk_bf16_f32 v116, v54, v55
	v_cvt_pk_bf16_f32 v117, v56, v57
	v_cvt_pk_bf16_f32 v110, v58, v59
	v_cvt_pk_bf16_f32 v111, v60, v61
	v_cvt_pk_bf16_f32 v112, v62, v63
	v_cvt_pk_bf16_f32 v113, v64, v65
	s_branch .LBB0_189
.LBB0_188:
	v_mov_b32_e32 v1, v207
.LBB0_189:
	s_add_i32 s37, s47, -1
	s_sub_i32 s50, s50, 64
	s_addk_i32 s49, 0xc000
	s_cmp_lt_i32 s47, 1
	v_add_u32_e32 v175, 0xffffff00, v175
	s_cbranch_scc1 .LBB0_171
	s_mov_b32 s47, s37
	v_mov_b32_e32 v207, v1
	s_cmp_lt_u32 s47, 2
	s_mov_b64 s[38:39], -1
	s_cbranch_scc1 .LBB0_175
	s_branch .LBB0_176
